# stack of three small edits on the best kernel: permlane-swap cross-lane sums in ssd_out, 16-byte stores in the prologue x/p fast path, counted wait in the scan loop
# baseline (speedup 1.0000x reference)
; #define LAS __attribute__((address_space(3)))
; __device__ __forceinline__ unsigned cvt_pk_bf16(float lo, float hi) { unsigned r; asm volatile("v_cvt_pk_bf16_f32 %0, %1, %2" : "=v"(r) : "v"(lo), "v"(hi)); return r; }
; __device__ __forceinline__ float bflo(unsigned w) { return __uint_as_float(w << 16); }
; __device__ __forceinline__ float bfhi(unsigned w) { return __uint_as_float(w & 0xffff0000u); }
; __device__ void phase_ssd_out(KP P, int layer, LAS unsigned char* lds) {
;     ...
;                         const bf16x8 mf = pack8(mv);
;                         acc[u][0] = __builtin_amdgcn_mfma_f32_16x16x32_bf16(bx0, mf, acc[u][0], 0, 0, 0);
;                         acc[u][1] = __builtin_amdgcn_mfma_f32_16x16x32_bf16(bx1, mf, acc[u][1], 0, 0, 0); }
;                 }
; #pragma unroll
;                 for (int u = 0; u < 2; ++u) { const int lt = 2 * ltp + u; const f32x4 acc0 = acc[u][0], acc1 = acc[u][1]; const u32x2 z0 = zv[u][0], z1 = zv[u][1];
;                   float s0, s1, s2, s3, s4, s5, s6, s7;
;                   sigmoid2(bflo(z0.x), bfhi(z0.x), s0, s1); sigmoid2(bflo(z0.y), bfhi(z0.y), s2, s3); sigmoid2(bflo(z1.x), bfhi(z1.x), s4, s5); sigmoid2(bflo(z1.y), bfhi(z1.y), s6, s7);
;                   const float y0 = acc0[0] * bflo(z0.x) * s0, y1 = acc0[1] * bfhi(z0.x) * s1, y2 = acc0[2] * bflo(z0.y) * s2, y3 = acc0[3] * bfhi(z0.y) * s3;
;                   const float y4 = acc1[0] * bflo(z1.x) * s4, y5 = acc1[1] * bfhi(z1.x) * s5, y6 = acc1[2] * bflo(z1.y) * s6, y7 = acc1[3] * bfhi(z1.y) * s7;
;                   bf16_t* zp = zl + (long)lt * 16 * PW;
;                   u32x2 o0, o1; o0.x = cvt_pk_bf16(y0, y1); o0.y = cvt_pk_bf16(y2, y3); o1.x = cvt_pk_bf16(y4, y5); o1.y = cvt_pk_bf16(y6, y7);
;                   *(u32x2*)zp = o0; *(u32x2*)(zp + 16) = o1;
;                   float sq = (y0 * y0 + y1 * y1) + (y2 * y2 + y3 * y3) + (y4 * y4 + y5 * y5) + (y6 * y6 + y7 * y7);
;                   sq += __shfl_xor(sq, 16); sq += __shfl_xor(sq, 32);
;                   if (q == 0) { LAS float* rp = red + wid * 128 + lrow[u]; *rp = (ph == 0) ? sq : (*rp + sq); } }
.LBB0_41:
	v_cvt_pk_bf16_f32 v28, v8, v9
	v_cvt_pk_bf16_f32 v29, v44, v45
	v_cvt_pk_bf16_f32 v30, v10, v11
	v_cvt_pk_bf16_f32 v31, v46, v47
	s_waitcnt vmcnt(1)
	v_permlane16_swap_b32 v60, v62
	v_permlane16_swap_b32 v61, v63
	s_nop 1
	v_and_b32_e32 v34, 0xffff0000, v62
	v_mfma_f32_16x16x32_bf16 v[8:11], v[16:19], v[28:31], v[0:3]
	v_lshlrev_b32_e32 v17, 16, v63
	v_max_f32_e64 v16, -v17, -v17
	v_min_f32_e32 v16, 0x42200000, v16
	v_mfma_f32_16x16x32_bf16 v[0:3], v[20:23], v[28:31], v[4:7]
	v_and_b32_e32 v35, 0xffff0000, v63
	v_mul_f32_e32 v16, 0x3fb8aa3b, v16
	s_waitcnt vmcnt(1)
	v_lshlrev_b32_e32 v21, 16, v60
	v_lshlrev_b32_e32 v5, 16, v62
	v_max_f32_e64 v4, -v5, -v5
	v_min_f32_e32 v4, 0x42200000, v4
	v_mul_f32_e32 v4, 0x3fb8aa3b, v4
	v_exp_f32_e32 v6, v4
	v_max_f32_e64 v4, -v34, -v34
	v_min_f32_e32 v4, 0x42200000, v4
	v_mul_f32_e32 v4, 0x3fb8aa3b, v4
	v_exp_f32_e32 v7, v4
	v_exp_f32_e32 v18, v16
	v_max_f32_e64 v16, -v35, -v35
	v_max_f32_e64 v20, -v21, -v21
	v_min_f32_e32 v16, 0x42200000, v16
	v_min_f32_e32 v20, 0x42200000, v20
	v_mul_f32_e32 v16, 0x3fb8aa3b, v16
	v_and_b32_e32 v36, 0xffff0000, v60
	v_mul_f32_e32 v20, 0x3fb8aa3b, v20
	v_lshlrev_b32_e32 v29, 16, v61
	v_exp_f32_e32 v19, v16
	v_exp_f32_e32 v22, v20
	v_max_f32_e64 v20, -v36, -v36
	v_max_f32_e64 v28, -v29, -v29
	v_pk_add_f32 v[6:7], v[6:7], 1.0 op_sel_hi:[1,0]
	v_min_f32_e32 v20, 0x42200000, v20
	v_min_f32_e32 v28, 0x42200000, v28
	v_mul_f32_e32 v4, v6, v7
	v_mul_f32_e32 v20, 0x3fb8aa3b, v20
	v_and_b32_e32 v37, 0xffff0000, v61
	v_mul_f32_e32 v28, 0x3fb8aa3b, v28
	v_rcp_f32_e32 v4, v4
	v_exp_f32_e32 v23, v20
	v_exp_f32_e32 v30, v28
	v_max_f32_e64 v28, -v37, -v37
	v_pk_add_f32 v[18:19], v[18:19], 1.0 op_sel_hi:[1,0]
	v_min_f32_e32 v28, 0x42200000, v28
	v_mul_f32_e32 v16, v18, v19
	v_mul_f32_e32 v28, 0x3fb8aa3b, v28
	v_rcp_f32_e32 v16, v16
	v_exp_f32_e32 v31, v28
	v_mov_b32_e32 v32, v7
	v_mov_b32_e32 v33, v24
	v_pk_add_f32 v[22:23], v[22:23], 1.0 op_sel_hi:[1,0]
	v_pk_mul_f32 v[32:33], v[32:33], v[4:5]
	v_mov_b32_e32 v7, v25
	v_mov_b32_e32 v5, v34
	v_mul_f32_e32 v20, v22, v23
	v_pk_mul_f32 v[4:5], v[6:7], v[4:5]
	v_rcp_f32_e32 v20, v20
	v_mul_f32_e32 v25, v4, v5
	v_mov_b32_e32 v4, v19
	v_mov_b32_e32 v5, v26
	v_pk_add_f32 v[30:31], v[30:31], 1.0 op_sel_hi:[1,0]
	v_pk_mul_f32 v[4:5], v[4:5], v[16:17]
	v_mov_b32_e32 v19, v27
	v_mov_b32_e32 v17, v35
	v_mul_f32_e32 v28, v30, v31
	v_mul_f32_e32 v26, v4, v5
	v_pk_mul_f32 v[4:5], v[18:19], v[16:17]
	v_rcp_f32_e32 v28, v28
	v_mul_f32_e32 v16, v4, v5
	v_mov_b32_e32 v4, v23
	v_mov_b32_e32 v5, v12
	v_pk_mul_f32 v[4:5], v[4:5], v[20:21]
	v_mov_b32_e32 v23, v13
	v_mov_b32_e32 v21, v36
	v_mul_f32_e32 v12, v4, v5
	v_pk_mul_f32 v[4:5], v[22:23], v[20:21]
	v_mul_f32_e32 v24, v32, v33
	v_mul_f32_e32 v13, v4, v5
	v_mov_b32_e32 v4, v31
	v_mov_b32_e32 v5, v14
	v_pk_mul_f32 v[4:5], v[4:5], v[28:29]
	v_mov_b32_e32 v31, v15
	v_mov_b32_e32 v29, v37
	v_mul_f32_e32 v14, v4, v5
	v_pk_mul_f32 v[4:5], v[30:31], v[28:29]
	s_nop 0
	v_mul_f32_e32 v15, v4, v5
	v_cvt_pk_bf16_f32 v4, v24, v25
	v_cvt_pk_bf16_f32 v5, v26, v16
	v_cvt_pk_bf16_f32 v6, v12, v13
	v_cvt_pk_bf16_f32 v7, v14, v15
	v_and_b32_e32 v30, 4, v156
	v_mul_u32_u24_e32 v30, 6, v30
	v_mov_b32_e32 v31, 0
	v_permlane16_swap_b32 v4, v6
	v_permlane16_swap_b32 v5, v7
	v_lshl_add_u64 v[30:31], v[58:59], 0, v[30:31]
	global_store_dwordx4 v[30:31], v[4:7], off offset:2560
	s_nop 1
	v_mul_f32_e32 v4, v26, v26
	v_mul_f32_e32 v5, v24, v24
	v_fmac_f32_e32 v4, v16, v16
	v_fmac_f32_e32 v5, v25, v25
	v_add_f32_e32 v4, v5, v4
	v_mul_f32_e32 v5, v12, v12
	v_fmac_f32_e32 v5, v13, v13
	v_add_f32_e32 v4, v4, v5
	v_mul_f32_e32 v5, v14, v14
	v_fmac_f32_e32 v5, v15, v15
	v_add_f32_e32 v4, v5, v4
	v_mov_b32_e32 v5, v4
	s_nop 1
	v_permlane16_swap_b32 v5, v4
	s_nop 1
	v_add_f32_e32 v4, v4, v5
	v_mov_b32_e32 v5, v4
	s_nop 1
	v_permlane32_swap_b32 v5, v4
	s_nop 1
	s_and_saveexec_b64 s[12:13], s[40:41]
	s_cbranch_execz .LBB0_45
	s_andn2_b64 vcc, exec, s[10:11]
	s_waitcnt lgkmcnt(0)
	v_add_f32_e32 v4, v4, v5
	s_cbranch_vccnz .LBB0_44
	ds_read_b32 v5, v79 offset:45056
	s_waitcnt lgkmcnt(0)
	v_add_f32_e32 v4, v4, v5

; #define LAS __attribute__((address_space(3)))
; __device__ __forceinline__ unsigned cvt_pk_bf16(float lo, float hi) { unsigned r; asm volatile("v_cvt_pk_bf16_f32 %0, %1, %2" : "=v"(r) : "v"(lo), "v"(hi)); return r; }
; __device__ __forceinline__ float bflo(unsigned w) { return __uint_as_float(w << 16); }
; __device__ __forceinline__ float bfhi(unsigned w) { return __uint_as_float(w & 0xffff0000u); }
; __device__ void phase_ssd_out(KP P, int layer, LAS unsigned char* lds) {
;     ...
;                 for (int u = 0; u < 2; ++u) { const int lt = 2 * ltp + u; const f32x4 acc0 = acc[u][0], acc1 = acc[u][1]; const u32x2 z0 = zv[u][0], z1 = zv[u][1];
;                   float s0, s1, s2, s3, s4, s5, s6, s7;
;                   sigmoid2(bflo(z0.x), bfhi(z0.x), s0, s1); sigmoid2(bflo(z0.y), bfhi(z0.y), s2, s3); sigmoid2(bflo(z1.x), bfhi(z1.x), s4, s5); sigmoid2(bflo(z1.y), bfhi(z1.y), s6, s7);
;                   const float y0 = acc0[0] * bflo(z0.x) * s0, y1 = acc0[1] * bfhi(z0.x) * s1, y2 = acc0[2] * bflo(z0.y) * s2, y3 = acc0[3] * bfhi(z0.y) * s3;
;                   const float y4 = acc1[0] * bflo(z1.x) * s4, y5 = acc1[1] * bfhi(z1.x) * s5, y6 = acc1[2] * bflo(z1.y) * s6, y7 = acc1[3] * bfhi(z1.y) * s7;
;                   bf16_t* zp = zl + (long)lt * 16 * PW;
;                   u32x2 o0, o1; o0.x = cvt_pk_bf16(y0, y1); o0.y = cvt_pk_bf16(y2, y3); o1.x = cvt_pk_bf16(y4, y5); o1.y = cvt_pk_bf16(y6, y7);
;                   *(u32x2*)zp = o0; *(u32x2*)(zp + 16) = o1;
;                   float sq = (y0 * y0 + y1 * y1) + (y2 * y2 + y3 * y3) + (y4 * y4 + y5 * y5) + (y6 * y6 + y7 * y7);
;                   sq += __shfl_xor(sq, 16); sq += __shfl_xor(sq, 32);
;                   if (q == 0) { LAS float* rp = red + wid * 128 + lrow[u]; *rp = (ph == 0) ? sq : (*rp + sq); } }
.LBB0_45:
	s_or_b64 exec, exec, s[12:13]
	s_waitcnt vmcnt(1) lgkmcnt(0)
	v_permlane16_swap_b32 v54, v56
	v_permlane16_swap_b32 v55, v57
	s_nop 1
	v_lshlrev_b32_e32 v5, 16, v56
	v_max_f32_e64 v4, -v5, -v5
	v_min_f32_e32 v4, 0x42200000, v4
	v_and_b32_e32 v26, 0xffff0000, v56
	v_mul_f32_e32 v4, 0x3fb8aa3b, v4
	v_exp_f32_e32 v6, v4
	v_max_f32_e64 v4, -v26, -v26
	v_min_f32_e32 v4, 0x42200000, v4
	v_mul_f32_e32 v4, 0x3fb8aa3b, v4
	v_lshlrev_b32_e32 v13, 16, v57
	s_waitcnt vmcnt(1)
	v_lshlrev_b32_e32 v17, 16, v54
	v_exp_f32_e32 v7, v4
	v_max_f32_e64 v4, -v13, -v13
	v_max_f32_e64 v16, -v17, -v17
	v_min_f32_e32 v4, 0x42200000, v4
	v_min_f32_e32 v16, 0x42200000, v16
	v_and_b32_e32 v27, 0xffff0000, v57
	v_mul_f32_e32 v4, 0x3fb8aa3b, v4
	v_and_b32_e32 v28, 0xffff0000, v54
	v_mul_f32_e32 v16, 0x3fb8aa3b, v16
	v_exp_f32_e32 v14, v4
	v_max_f32_e64 v4, -v27, -v27
	v_exp_f32_e32 v18, v16
	v_max_f32_e64 v16, -v28, -v28
	v_min_f32_e32 v4, 0x42200000, v4
	v_min_f32_e32 v16, 0x42200000, v16
	v_mul_f32_e32 v4, 0x3fb8aa3b, v4
	v_mul_f32_e32 v16, 0x3fb8aa3b, v16
	v_lshlrev_b32_e32 v21, 16, v55
	v_exp_f32_e32 v15, v4
	v_exp_f32_e32 v19, v16
	v_max_f32_e64 v16, -v21, -v21
	v_pk_add_f32 v[6:7], v[6:7], 1.0 op_sel_hi:[1,0]
	v_min_f32_e32 v16, 0x42200000, v16
	v_mul_f32_e32 v4, v6, v7
	v_and_b32_e32 v29, 0xffff0000, v55
	v_mul_f32_e32 v16, 0x3fb8aa3b, v16
	v_rcp_f32_e32 v4, v4
	v_exp_f32_e32 v22, v16
	v_max_f32_e64 v16, -v29, -v29
	v_pk_add_f32 v[14:15], v[14:15], 1.0 op_sel_hi:[1,0]
	v_min_f32_e32 v16, 0x42200000, v16
	v_mul_f32_e32 v12, v14, v15
	v_mul_f32_e32 v16, 0x3fb8aa3b, v16
	v_rcp_f32_e32 v12, v12
	v_exp_f32_e32 v23, v16
	v_mov_b32_e32 v24, v7
	v_mov_b32_e32 v25, v8
	v_pk_add_f32 v[18:19], v[18:19], 1.0 op_sel_hi:[1,0]
	v_pk_mul_f32 v[24:25], v[24:25], v[4:5]
	v_mov_b32_e32 v7, v9
	v_mov_b32_e32 v5, v26
	v_mul_f32_e32 v16, v18, v19
	v_pk_mul_f32 v[4:5], v[6:7], v[4:5]
	v_rcp_f32_e32 v16, v16
	v_mul_f32_e32 v6, v4, v5
	v_mov_b32_e32 v4, v15
	v_mov_b32_e32 v5, v10
	v_pk_add_f32 v[22:23], v[22:23], 1.0 op_sel_hi:[1,0]
	v_pk_mul_f32 v[4:5], v[4:5], v[12:13]
	v_mov_b32_e32 v15, v11
	v_mov_b32_e32 v13, v27
	v_mul_f32_e32 v20, v22, v23
	v_mul_f32_e32 v7, v4, v5
	v_pk_mul_f32 v[4:5], v[14:15], v[12:13]
	v_rcp_f32_e32 v20, v20
	v_mul_f32_e32 v9, v4, v5
	v_mov_b32_e32 v4, v19
	v_mov_b32_e32 v5, v0
	v_pk_mul_f32 v[4:5], v[4:5], v[16:17]
	v_mov_b32_e32 v19, v1
	v_mov_b32_e32 v17, v28
	v_pk_mul_f32 v[0:1], v[18:19], v[16:17]
	v_mul_f32_e32 v4, v4, v5
	v_mul_f32_e32 v5, v0, v1
	v_mov_b32_e32 v0, v23
	v_mov_b32_e32 v1, v2
	v_pk_mul_f32 v[0:1], v[0:1], v[20:21]
	v_mov_b32_e32 v23, v3
	v_mov_b32_e32 v21, v29
	v_mul_f32_e32 v8, v24, v25
	v_mul_f32_e32 v10, v0, v1
	v_pk_mul_f32 v[0:1], v[22:23], v[20:21]
	v_mul_f32_e32 v2, v8, v8
	v_mul_f32_e32 v0, v0, v1
	v_mul_f32_e32 v1, v7, v7
	v_fmac_f32_e32 v1, v9, v9
	v_fmac_f32_e32 v2, v6, v6
	v_add_f32_e32 v1, v2, v1
	v_mul_f32_e32 v2, v4, v4
	v_fmac_f32_e32 v2, v5, v5
	v_add_f32_e32 v1, v1, v2
	v_mul_f32_e32 v2, v10, v10
	v_fmac_f32_e32 v2, v0, v0
	v_add_f32_e32 v1, v2, v1
	v_mov_b32_e32 v11, v1
	s_nop 1
	v_permlane16_swap_b32 v11, v1
	v_cvt_pk_bf16_f32 v2, v8, v6
	v_cvt_pk_bf16_f32 v3, v7, v9
	v_cvt_pk_bf16_f32 v4, v4, v5
	v_cvt_pk_bf16_f32 v5, v10, v0
	s_waitcnt lgkmcnt(0)
	v_add_f32_e32 v0, v1, v11
	v_mov_b32_e32 v1, v0
	s_nop 1
	v_permlane32_swap_b32 v1, v0
	s_nop 1
	v_add_co_u32_e32 v6, vcc, s77, v68
	s_nop 1
	v_addc_co_u32_e32 v7, vcc, 0, v69, vcc
	v_and_b32_e32 v11, 4, v156
	v_mul_u32_u24_e32 v11, 6, v11
	v_permlane16_swap_b32 v2, v4
	v_permlane16_swap_b32 v3, v5
	v_add_co_u32_e32 v6, vcc, v6, v11
	s_nop 1
	v_addc_co_u32_e32 v7, vcc, 0, v7, vcc
	global_store_dwordx4 v[6:7], v[2:5], off
	s_nop 1
	s_and_saveexec_b64 s[12:13], s[40:41]
	s_cbranch_execz .LBB0_28
	s_andn2_b64 vcc, exec, s[10:11]
	s_waitcnt lgkmcnt(0)
	v_add_f32_e32 v0, v0, v1
	s_cbranch_vccnz .LBB0_27
	ds_read_b32 v1, v78 offset:45056
	s_waitcnt lgkmcnt(0)
	v_add_f32_e32 v0, v0, v1
	s_branch .LBB0_27

; __device__ __forceinline__ unsigned cvt_pk_bf16(float lo, float hi) { unsigned r; asm volatile("v_cvt_pk_bf16_f32 %0, %1, %2" : "=v"(r) : "v"(lo), "v"(hi)); return r; }
; __device__ __forceinline__ float bflo(unsigned w) { return __uint_as_float(w << 16); }
; __device__ __forceinline__ float bfhi(unsigned w) { return __uint_as_float(w & 0xffff0000u); }
; __device__ void phase_scan_sc(KP P, int layer) {
;     ...
;         for (int c0 = 0; c0 < 64; c0 += 16) { unsigned s[16]; float d[16];
; #pragma unroll
;             for (int i = 0; i < 16; ++i) { s[i] = p[(size_t)(c0 + i) * 32768]; d[i] = __expf(totals[(b * 64 + c0 + i) * 16 + h]); }
; #pragma unroll
;             for (int i = 0; i < 16; ++i) { p[(size_t)(c0 + i) * 32768] = cvt_pk_bf16(r0, r1); r0 = d[i] * r0 + bflo(s[i]); r1 = d[i] * r1 + bfhi(s[i]); } }
.LBB0_54:
	s_waitcnt lgkmcnt(0)
	v_lshl_add_u64 v[6:7], s[90:91], 0, v[0:1]
	v_add_co_u32_e32 v30, vcc, 0x1dd08000, v6
	v_lshl_add_u64 v[8:9], s[90:91], 0, v[2:3]
	s_nop 0
	v_addc_co_u32_e32 v31, vcc, 0, v7, vcc
	v_add_co_u32_e32 v32, vcc, 0x8d00000, v8
	global_load_dword v42, v[30:31], off
	s_nop 0
	v_addc_co_u32_e32 v33, vcc, 0, v9, vcc
	v_add_co_u32_e32 v24, vcc, 0x1dd28000, v6
	global_load_dword v43, v[32:33], off
	global_load_dword v44, v[32:33], off offset:64
	global_load_dword v45, v[32:33], off offset:128
	global_load_dword v46, v[32:33], off offset:192
	global_load_dword v47, v[32:33], off offset:256
	global_load_dword v48, v[32:33], off offset:320
	global_load_dword v49, v[32:33], off offset:384
	global_load_dword v50, v[32:33], off offset:448
	global_load_dword v51, v[32:33], off offset:512
	global_load_dword v52, v[32:33], off offset:576
	global_load_dword v53, v[32:33], off offset:640
	global_load_dword v54, v[32:33], off offset:704
	global_load_dword v55, v[32:33], off offset:768
	global_load_dword v56, v[32:33], off offset:832
	global_load_dword v57, v[32:33], off offset:896
	v_addc_co_u32_e32 v25, vcc, 0, v7, vcc
	v_add_co_u32_e32 v8, vcc, 0x1dd48000, v6
	s_mov_b64 s[10:11], 0x400
	s_nop 0
	v_addc_co_u32_e32 v9, vcc, 0, v7, vcc
	v_add_co_u32_e32 v20, vcc, 0x1dd68000, v6
	global_load_dword v59, v[24:25], off
	global_load_dword v61, v[8:9], off
	v_addc_co_u32_e32 v21, vcc, 0, v7, vcc
	v_add_co_u32_e32 v22, vcc, 0x1dd88000, v6
	v_lshl_add_u64 v[2:3], v[2:3], 0, s[10:11]
	s_nop 0
	v_addc_co_u32_e32 v23, vcc, 0, v7, vcc
	v_add_co_u32_e32 v16, vcc, 0x1dda8000, v6
	global_load_dword v63, v[20:21], off
	global_load_dword v65, v[22:23], off
	v_addc_co_u32_e32 v17, vcc, 0, v7, vcc
	v_add_co_u32_e32 v18, vcc, 0x1ddc8000, v6
	s_add_i32 s5, s5, 16
	s_nop 0
	v_addc_co_u32_e32 v19, vcc, 0, v7, vcc
	v_add_co_u32_e32 v12, vcc, 0x1dde8000, v6
	global_load_dword v67, v[16:17], off
	global_load_dword v69, v[18:19], off
	v_addc_co_u32_e32 v13, vcc, 0, v7, vcc
	v_add_co_u32_e32 v14, vcc, 0x1de08000, v6
	global_load_dword v71, v[12:13], off
	global_load_dword v80, v[32:33], off offset:960
	v_addc_co_u32_e32 v15, vcc, 0, v7, vcc
	v_add_co_u32_e32 v10, vcc, 0x1de28000, v6
	s_mov_b64 s[10:11], 0x200000
	s_nop 0
	v_addc_co_u32_e32 v11, vcc, 0, v7, vcc
	v_add_co_u32_e32 v32, vcc, 0x1de48000, v6
	global_load_dword v81, v[14:15], off
	global_load_dword v82, v[10:11], off
	v_addc_co_u32_e32 v33, vcc, 0, v7, vcc
	v_add_co_u32_e32 v34, vcc, 0x1de68000, v6
	v_lshl_add_u64 v[0:1], v[0:1], 0, s[10:11]
	s_nop 0
	v_addc_co_u32_e32 v35, vcc, 0, v7, vcc
	v_add_co_u32_e32 v36, vcc, 0x1de88000, v6
	global_load_dword v83, v[32:33], off
	global_load_dword v84, v[34:35], off
	v_addc_co_u32_e32 v37, vcc, 0, v7, vcc
	v_add_co_u32_e32 v38, vcc, 0x1dea8000, v6
	s_cmp_gt_u32 s5, 47
	s_nop 0
	v_addc_co_u32_e32 v39, vcc, 0, v7, vcc
	v_add_co_u32_e32 v40, vcc, 0x1dec8000, v6
	global_load_dword v85, v[36:37], off
	global_load_dword v86, v[38:39], off
	v_addc_co_u32_e32 v41, vcc, 0, v7, vcc
	v_add_co_u32_e32 v6, vcc, 0x1dee8000, v6
	s_waitcnt vmcnt(26)
	v_mul_f32_e32 v45, 0x3fb8aa3b, v45
	v_addc_co_u32_e32 v7, vcc, 0, v7, vcc
	global_load_dword v87, v[40:41], off
	global_load_dword v88, v[6:7], off
	v_cvt_pk_bf16_f32 v58, v4, v5
	global_store_dword v[30:31], v58, off
	v_lshlrev_b32_e32 v30, 16, v42
	v_and_b32_e32 v31, 0xffff0000, v42
	v_mul_f32_e32 v42, 0x3fb8aa3b, v43
	v_mul_f32_e32 v43, 0x3fb8aa3b, v44
	v_exp_f32_e32 v42, v42
	v_exp_f32_e32 v44, v43
	s_waitcnt vmcnt(28)
	v_mul_f32_e32 v58, 0x3fb8aa3b, v46
	v_exp_f32_e32 v46, v45
	s_waitcnt vmcnt(27)
	v_mul_f32_e32 v47, 0x3fb8aa3b, v47
	s_waitcnt vmcnt(26)
	v_mul_f32_e32 v60, 0x3fb8aa3b, v48
	v_exp_f32_e32 v48, v58
	s_waitcnt vmcnt(24)
	v_mul_f32_e32 v62, 0x3fb8aa3b, v50
	v_exp_f32_e32 v50, v47
	s_waitcnt vmcnt(16)
	v_lshlrev_b32_e32 v72, 16, v59
	v_and_b32_e32 v73, 0xffff0000, v59
	v_pk_fma_f32 v[4:5], v[4:5], v[42:43], v[30:31] op_sel_hi:[1,0,1]
	v_mul_f32_e32 v49, 0x3fb8aa3b, v49
	v_mul_f32_e32 v64, 0x3fb8aa3b, v52
	v_exp_f32_e32 v52, v60
	s_waitcnt vmcnt(15)
; __device__ __forceinline__ unsigned cvt_pk_bf16(float lo, float hi) { unsigned r; asm volatile("v_cvt_pk_bf16_f32 %0, %1, %2" : "=v"(r) : "v"(lo), "v"(hi)); return r; }
; __device__ __forceinline__ float bflo(unsigned w) { return __uint_as_float(w << 16); }
; __device__ __forceinline__ float bfhi(unsigned w) { return __uint_as_float(w & 0xffff0000u); }
; __device__ void phase_scan_sc(KP P, int layer) {
;     ...
;     for (int e2 = gtid; e2 < 131072; e2 += gthreads) {
;         const int b = e2 >> 15, rem = (e2 & 32767) * 2, h = rem >> 12;
;         unsigned* p = (unsigned*)(states + (size_t)b * 64 * 65536 + rem);
;         float r0 = 0.f, r1 = 0.f;
;         for (int c0 = 0; c0 < 64; c0 += 16) { unsigned s[16]; float d[16];
; #pragma unroll
;             for (int i = 0; i < 16; ++i) { s[i] = p[(size_t)(c0 + i) * 32768]; d[i] = __expf(totals[(b * 64 + c0 + i) * 16 + h]); }
; #pragma unroll
;             for (int i = 0; i < 16; ++i) { p[(size_t)(c0 + i) * 32768] = cvt_pk_bf16(r0, r1); r0 = d[i] * r0 + bflo(s[i]); r1 = d[i] * r1 + bfhi(s[i]); } }
	v_lshlrev_b32_e32 v74, 16, v61
	v_and_b32_e32 v75, 0xffff0000, v61
	v_cvt_pk_bf16_f32 v45, v4, v5
	v_mul_f32_e32 v66, 0x3fb8aa3b, v54
	v_pk_fma_f32 v[4:5], v[4:5], v[44:45], v[72:73] op_sel_hi:[1,0,1]
	v_exp_f32_e32 v54, v49
	s_waitcnt vmcnt(14)
	v_lshlrev_b32_e32 v76, 16, v63
	v_and_b32_e32 v77, 0xffff0000, v63
	global_store_dword v[24:25], v45, off
	v_cvt_pk_bf16_f32 v45, v4, v5
	v_pk_fma_f32 v[4:5], v[4:5], v[46:47], v[74:75] op_sel_hi:[1,0,1]
	v_mul_f32_e32 v51, 0x3fb8aa3b, v51
	v_mul_f32_e32 v68, 0x3fb8aa3b, v56
	v_exp_f32_e32 v56, v62
	s_waitcnt vmcnt(14)
	v_lshlrev_b32_e32 v78, 16, v65
	v_and_b32_e32 v79, 0xffff0000, v65
	global_store_dword v[8:9], v45, off
	v_cvt_pk_bf16_f32 v45, v4, v5
	v_pk_fma_f32 v[4:5], v[4:5], v[48:49], v[76:77] op_sel_hi:[1,0,1]
	v_mul_f32_e32 v53, 0x3fb8aa3b, v53
	v_exp_f32_e32 v58, v51
	s_waitcnt vmcnt(14)
	v_lshlrev_b32_e32 v30, 16, v67
	v_and_b32_e32 v31, 0xffff0000, v67
	global_store_dword v[20:21], v45, off
	v_cvt_pk_bf16_f32 v45, v4, v5
	v_pk_fma_f32 v[4:5], v[4:5], v[50:51], v[78:79] op_sel_hi:[1,0,1]
	v_mul_f32_e32 v55, 0x3fb8aa3b, v55
	v_exp_f32_e32 v60, v64
	s_waitcnt vmcnt(14)
	v_lshlrev_b32_e32 v42, 16, v69
	v_and_b32_e32 v43, 0xffff0000, v69
	global_store_dword v[22:23], v45, off
	v_cvt_pk_bf16_f32 v45, v4, v5
	v_pk_fma_f32 v[4:5], v[4:5], v[52:53], v[30:31] op_sel_hi:[1,0,1]
	v_mul_f32_e32 v57, 0x3fb8aa3b, v57
	v_exp_f32_e32 v62, v53
	s_waitcnt vmcnt(14)
	v_lshlrev_b32_e32 v24, 16, v71
	v_and_b32_e32 v25, 0xffff0000, v71
	global_store_dword v[16:17], v45, off
	v_cvt_pk_bf16_f32 v30, v4, v5
	v_pk_fma_f32 v[4:5], v[4:5], v[54:55], v[42:43] op_sel_hi:[1,0,1]
	v_exp_f32_e32 v64, v66
	s_waitcnt vmcnt(13)
	v_lshlrev_b32_e32 v8, 16, v81
	v_and_b32_e32 v9, 0xffff0000, v81
	global_store_dword v[18:19], v30, off
	v_cvt_pk_bf16_f32 v30, v4, v5
	v_pk_fma_f32 v[4:5], v[4:5], v[56:57], v[24:25] op_sel_hi:[1,0,1]
	v_exp_f32_e32 v66, v55
	s_waitcnt vmcnt(13)
	v_lshlrev_b32_e32 v20, 16, v82
	v_and_b32_e32 v21, 0xffff0000, v82
	global_store_dword v[12:13], v30, off
	v_cvt_pk_bf16_f32 v12, v4, v5
	v_pk_fma_f32 v[4:5], v[4:5], v[58:59], v[8:9] op_sel_hi:[1,0,1]
	v_exp_f32_e32 v68, v68
	s_waitcnt vmcnt(13)
	v_lshlrev_b32_e32 v22, 16, v83
	v_and_b32_e32 v23, 0xffff0000, v83
	global_store_dword v[14:15], v12, off
	v_cvt_pk_bf16_f32 v14, v4, v5
	v_pk_fma_f32 v[4:5], v[4:5], v[60:61], v[20:21] op_sel_hi:[1,0,1]
	v_exp_f32_e32 v70, v57
	v_mul_f32_e32 v44, 0x3fb8aa3b, v80
	s_waitcnt vmcnt(13)
	v_lshlrev_b32_e32 v16, 16, v84
	v_and_b32_e32 v17, 0xffff0000, v84
	global_store_dword v[10:11], v14, off
	v_cvt_pk_bf16_f32 v14, v4, v5
	v_pk_fma_f32 v[4:5], v[4:5], v[62:63], v[22:23] op_sel_hi:[1,0,1]
	v_exp_f32_e32 v44, v44
	s_waitcnt vmcnt(13)
	v_lshlrev_b32_e32 v18, 16, v85
	v_and_b32_e32 v19, 0xffff0000, v85
	global_store_dword v[32:33], v14, off
	v_cvt_pk_bf16_f32 v14, v4, v5
	v_pk_fma_f32 v[4:5], v[4:5], v[64:65], v[16:17] op_sel_hi:[1,0,1]
	s_waitcnt vmcnt(13)
	v_lshlrev_b32_e32 v8, 16, v86
	v_and_b32_e32 v9, 0xffff0000, v86
	global_store_dword v[34:35], v14, off
	v_cvt_pk_bf16_f32 v14, v4, v5
	v_pk_fma_f32 v[4:5], v[4:5], v[66:67], v[18:19] op_sel_hi:[1,0,1]
	s_waitcnt vmcnt(13)
	v_lshlrev_b32_e32 v12, 16, v87
	v_and_b32_e32 v13, 0xffff0000, v87
	global_store_dword v[36:37], v14, off
	v_cvt_pk_bf16_f32 v14, v4, v5
	v_pk_fma_f32 v[4:5], v[4:5], v[68:69], v[8:9] op_sel_hi:[1,0,1]
	s_waitcnt vmcnt(13)
	v_lshlrev_b32_e32 v10, 16, v88
	v_and_b32_e32 v11, 0xffff0000, v88
	global_store_dword v[38:39], v14, off
	v_cvt_pk_bf16_f32 v8, v4, v5
	v_pk_fma_f32 v[4:5], v[4:5], v[70:71], v[12:13] op_sel_hi:[1,0,1]
	global_store_dword v[40:41], v8, off
	v_cvt_pk_bf16_f32 v8, v4, v5
	v_pk_fma_f32 v[4:5], v[4:5], v[44:45], v[10:11] op_sel_hi:[1,0,1]
	global_store_dword v[6:7], v8, off
	s_cbranch_scc0 .LBB0_54
	v_add_u32_e32 v29, s4, v29
	s_mov_b32 s5, 0x1ffff
	v_cmp_lt_i32_e32 vcc, s5, v29
	s_or_b64 s[8:9], vcc, s[8:9]
	v_add_u32_e32 v27, s3, v27
	s_andn2_b64 exec, exec, s[8:9]
	s_cbranch_execnz .LBB0_53
